# stack (through merge-epilogue preload) + hand-scheduled unorm8 epilogue for the HALFN tile
# speedup vs baseline: 1.0038x; 1.0038x over previous
; __device__ __forceinline__ float sigmoid_f(float x) { return __builtin_amdgcn_rcpf(1.0f + __builtin_amdgcn_exp2f(-1.4426950409f * x)); }
;     __device__ __forceinline__ void body_gate(f32x4 (&acc)[2][2][4][2], const Unit& u, int wr, int wc, int fr, int fq, int gbase, const float (&rsv)[2][4]) const {
;         EPI_ROWS_BEGIN
;             const float rs = rsv[ai][m];
; #pragma unroll
;             for (int bj = 0; bj < 2; ++bj) { if (u.half != 0 && bj == 1) continue;
;                 const int gcol = gbase + (bj + (u.half == 2 ? 1 : 0)) * 128 + wc * 32 + 8 * fq;
;                 f32x4 v0 = acc[ai][bj][m][0] * rs, v1 = acc[ai][bj][m][1] * rs;
; #pragma unroll
;                 for (int j = 0; j < 4; ++j) { v0[j] = sigmoid_f(v0[j]); v1[j] = sigmoid_f(v1[j]); }
;                 u32x2 w; w.x = pk_unorm8(v0); w.y = pk_unorm8(v1);
;                 *(u32x2*)((unsigned char*)P + (size_t)row * ROWB + GATE_B0 + gcol) = w;
;     __device__ __forceinline__ void operator()(f32x4 (&acc)[2][2][4][2], const Unit& u, int wr, int wc, int fr, int fq) const {
;     ...
;         const int pn = u.pn + pn0;
;         if (pn < 8) body_pair<0>(acc, u, wr, wc, fr, fq, OQ + pn * 128, rsv);
;         else if (pn < 16) body_pair<1>(acc, u, wr, wc, fr, fq, OAB + (pn - 8) * 128, rsv);
;         else if (pn < 20) body<0>(acc, u, wr, wc, fr, fq, OBIN + (pn - 16) * 256, rsv);
;         else if (pn < 24) body<1>(acc, u, wr, wc, fr, fq, OBZ + (pn - 20) * 256, rsv);
;         else if (pn < 32) body_pair<2>(acc, u, wr, wc, fr, fq, OV + (pn - 24) * 128, rsv);
;         else if (pn < 36) body<1>(acc, u, wr, wc, fr, fq, OCZ + (pn - 32) * 256, rsv);
;         else body_gate(acc, u, wr, wc, fr, fq, (pn - 36) * 256, rsv);
.LBB0_245:
	s_cmp_gt_u32 s8, 15
	s_cbranch_scc0 .LBB0_263
	s_cmp_gt_u32 s8, 19
	s_cbranch_scc0 .LBB0_260
	s_cmp_gt_u32 s8, 23
	s_cbranch_scc0 .LBB0_257
	s_cmp_gt_u32 s8, 31
	s_cbranch_scc0 .LBB0_254
	v_pk_mul_f32 v[104:105], v[62:63], v[94:95] op_sel_hi:[1,0]
	s_lshl_b32 s9, s8, 8
	v_mul_f32_e32 v95, 0xbfb8aa3b, v104
	v_exp_f32_e32 v95, v95
	v_mad_i64_i32 v[98:99], s[4:5], v88, s33, 0
	s_cmp_gt_u32 s8, 35
	v_pk_mul_f32 v[100:101], v[64:65], v[94:95] op_sel_hi:[1,0]
	v_pk_mul_f32 v[96:97], v[60:61], v[94:95] op_sel_hi:[1,0]
	v_pk_mul_f32 v[102:103], v[58:59], v[94:95] op_sel_hi:[1,0]
	v_add_f32_e32 v95, 1.0, v95
	v_rcp_f32_e32 v106, v95
	v_lshlrev_b32_e32 v121, 3, v114
	s_mov_b64 s[4:5], -1
	v_lshl_add_u64 v[98:99], s[68:69], 0, v[98:99]
	v_mul_f32_e32 v122, 0xbfb8aa3b, v102
	v_mul_f32_e32 v120, 0xbfb8aa3b, v105
	v_mul_f32_e32 v119, 0xbfb8aa3b, v103
	v_mul_f32_e32 v118, 0xbfb8aa3b, v100
	v_mul_f32_e32 v117, 0xbfb8aa3b, v96
	v_mul_f32_e32 v116, 0xbfb8aa3b, v101
	v_mul_f32_e32 v115, 0xbfb8aa3b, v97
	s_cbranch_scc0 .LBB0_251
	s_cmp_eq_u32 s80, 2
	s_cselect_b32 s4, 0x80, 0
	s_or_b32 s4, s4, s79
	s_add_i32 s4, s4, s9
	s_lshr_b32 s98, s4, 7
	s_and_b32 s98, s98, 14
	s_bfe_u32 s99, s4, 0x10006
	s_or_b32 s98, s98, s99
	v_sub_u32_e32 v182, s98, v1
	s_lshr_b32 s98, s4, 11
	s_lshl_b32 s98, s98, 11
	s_and_b32 s99, s4, 128
	s_lshl_b32 s99, s99, 3
	s_add_i32 s98, s98, s99
	s_and_b32 s99, s4, 32
	s_lshl_b32 s99, s99, 4
	s_add_i32 s98, s98, s99
	s_addk_i32 s98, 0x3000
	v_lshl_add_u32 v180, v114, 7, s98
	v_lshl_add_u32 v180, v1, 3, v180
	v_mad_i32_i24 v180, v182, s33, v180
	v_ashrrev_i32_e32 v181, 31, v180
	v_lshl_add_u64 v[178:179], s[68:69], 0, v[180:181]
	s_mov_b32 s98, 0x437f0000
	v_mul_f32_e32 v94, 0xbfb8aa3b, v94
	v_mul_f32_e32 v92, 0xbfb8aa3b, v92
	v_mul_f32_e32 v90, 0xbfb8aa3b, v90
	v_mul_f32_e32 v86, 0xbfb8aa3b, v86
	v_mul_f32_e32 v84, 0xbfb8aa3b, v84
	v_mul_f32_e32 v82, 0xbfb8aa3b, v82
	v_mul_f32_e32 v80, 0xbfb8aa3b, v80
	v_mul_f32_e32 v78, 0xbfb8aa3b, v78
	v_mad_i64_i32 v[174:175], s[4:5], v88, s33, v[178:179]
	v_pk_mul_f32 v[62:63], v[62:63], v[94:95] op_sel_hi:[1,0]
	v_pk_mul_f32 v[64:65], v[64:65], v[94:95] op_sel_hi:[1,0]
	v_pk_mul_f32 v[58:59], v[58:59], v[94:95] op_sel_hi:[1,0]
	v_pk_mul_f32 v[60:61], v[60:61], v[94:95] op_sel_hi:[1,0]
	v_exp_f32_e32 v62, v62
	v_exp_f32_e32 v63, v63
	v_exp_f32_e32 v64, v64
	v_exp_f32_e32 v65, v65
	v_exp_f32_e32 v58, v58
	v_exp_f32_e32 v59, v59
	v_exp_f32_e32 v60, v60
	v_exp_f32_e32 v61, v61
	v_pk_add_f32 v[62:63], v[62:63], 1.0 op_sel_hi:[1,0]
	v_pk_add_f32 v[64:65], v[64:65], 1.0 op_sel_hi:[1,0]
	v_pk_add_f32 v[58:59], v[58:59], 1.0 op_sel_hi:[1,0]
	v_pk_add_f32 v[60:61], v[60:61], 1.0 op_sel_hi:[1,0]
	v_rcp_f32_e32 v62, v62
	v_rcp_f32_e32 v63, v63
	v_rcp_f32_e32 v64, v64
	v_rcp_f32_e32 v65, v65
	v_rcp_f32_e32 v58, v58
	v_rcp_f32_e32 v59, v59
	v_rcp_f32_e32 v60, v60
	v_rcp_f32_e32 v61, v61
	v_pk_fma_f32 v[62:63], v[62:63], s[98:99], 0.5 op_sel_hi:[1,0,0]
	v_pk_fma_f32 v[64:65], v[64:65], s[98:99], 0.5 op_sel_hi:[1,0,0]
	v_pk_fma_f32 v[58:59], v[58:59], s[98:99], 0.5 op_sel_hi:[1,0,0]
	v_pk_fma_f32 v[60:61], v[60:61], s[98:99], 0.5 op_sel_hi:[1,0,0]
	v_cvt_u32_f32_e32 v170, v62
	v_cvt_u32_f32_e32 v171, v58
	v_cvt_u32_f32_sdwa v170, v63 dst_sel:BYTE_1 dst_unused:UNUSED_PRESERVE src0_sel:DWORD
	v_cvt_u32_f32_sdwa v171, v59 dst_sel:BYTE_1 dst_unused:UNUSED_PRESERVE src0_sel:DWORD
	v_cvt_u32_f32_sdwa v170, v64 dst_sel:BYTE_2 dst_unused:UNUSED_PRESERVE src0_sel:DWORD
	v_cvt_u32_f32_sdwa v171, v60 dst_sel:BYTE_2 dst_unused:UNUSED_PRESERVE src0_sel:DWORD
	v_cvt_u32_f32_sdwa v170, v65 dst_sel:BYTE_3 dst_unused:UNUSED_PRESERVE src0_sel:DWORD
	v_cvt_u32_f32_sdwa v171, v61 dst_sel:BYTE_3 dst_unused:UNUSED_PRESERVE src0_sel:DWORD
	s_nop 1
	global_store_dwordx2 v[174:175], v[170:171], off nt
	v_mad_i64_i32 v[176:177], s[4:5], v113, s33, v[178:179]
	v_pk_mul_f32 v[54:55], v[54:55], v[92:93] op_sel_hi:[1,0]
	v_pk_mul_f32 v[56:57], v[56:57], v[92:93] op_sel_hi:[1,0]
	v_pk_mul_f32 v[50:51], v[50:51], v[92:93] op_sel_hi:[1,0]
	v_pk_mul_f32 v[52:53], v[52:53], v[92:93] op_sel_hi:[1,0]
	v_exp_f32_e32 v54, v54
	v_exp_f32_e32 v55, v55
	v_exp_f32_e32 v56, v56
	v_exp_f32_e32 v57, v57
	v_exp_f32_e32 v50, v50
	v_exp_f32_e32 v51, v51
	v_exp_f32_e32 v52, v52
	v_exp_f32_e32 v53, v53
	v_pk_add_f32 v[54:55], v[54:55], 1.0 op_sel_hi:[1,0]
	v_pk_add_f32 v[56:57], v[56:57], 1.0 op_sel_hi:[1,0]
	v_pk_add_f32 v[50:51], v[50:51], 1.0 op_sel_hi:[1,0]
	v_pk_add_f32 v[52:53], v[52:53], 1.0 op_sel_hi:[1,0]
	v_rcp_f32_e32 v54, v54
	v_rcp_f32_e32 v55, v55
	v_rcp_f32_e32 v56, v56
	v_rcp_f32_e32 v57, v57
	v_rcp_f32_e32 v50, v50
	v_rcp_f32_e32 v51, v51
	v_rcp_f32_e32 v52, v52
	v_rcp_f32_e32 v53, v53
	v_pk_fma_f32 v[54:55], v[54:55], s[98:99], 0.5 op_sel_hi:[1,0,0]
	v_pk_fma_f32 v[56:57], v[56:57], s[98:99], 0.5 op_sel_hi:[1,0,0]
	v_pk_fma_f32 v[50:51], v[50:51], s[98:99], 0.5 op_sel_hi:[1,0,0]
	v_pk_fma_f32 v[52:53], v[52:53], s[98:99], 0.5 op_sel_hi:[1,0,0]
	v_cvt_u32_f32_e32 v172, v54
	v_cvt_u32_f32_e32 v173, v50
	v_cvt_u32_f32_sdwa v172, v55 dst_sel:BYTE_1 dst_unused:UNUSED_PRESERVE src0_sel:DWORD
	v_cvt_u32_f32_sdwa v173, v51 dst_sel:BYTE_1 dst_unused:UNUSED_PRESERVE src0_sel:DWORD
	v_cvt_u32_f32_sdwa v172, v56 dst_sel:BYTE_2 dst_unused:UNUSED_PRESERVE src0_sel:DWORD
	v_cvt_u32_f32_sdwa v173, v52 dst_sel:BYTE_2 dst_unused:UNUSED_PRESERVE src0_sel:DWORD
	v_cvt_u32_f32_sdwa v172, v57 dst_sel:BYTE_3 dst_unused:UNUSED_PRESERVE src0_sel:DWORD
	v_cvt_u32_f32_sdwa v173, v53 dst_sel:BYTE_3 dst_unused:UNUSED_PRESERVE src0_sel:DWORD
	s_nop 1
	global_store_dwordx2 v[176:177], v[172:173], off nt
	v_mad_i64_i32 v[174:175], s[4:5], v112, s33, v[178:179]
; __device__ __forceinline__ float sigmoid_f(float x) { return __builtin_amdgcn_rcpf(1.0f + __builtin_amdgcn_exp2f(-1.4426950409f * x)); }
;     __device__ __forceinline__ void body_gate(f32x4 (&acc)[2][2][4][2], const Unit& u, int wr, int wc, int fr, int fq, int gbase, const float (&rsv)[2][4]) const {
;     ...
;             const float rs = rsv[ai][m];
; #pragma unroll
;             for (int bj = 0; bj < 2; ++bj) { if (u.half != 0 && bj == 1) continue;
;                 const int gcol = gbase + (bj + (u.half == 2 ? 1 : 0)) * 128 + wc * 32 + 8 * fq;
;                 f32x4 v0 = acc[ai][bj][m][0] * rs, v1 = acc[ai][bj][m][1] * rs;
; #pragma unroll
;                 for (int j = 0; j < 4; ++j) { v0[j] = sigmoid_f(v0[j]); v1[j] = sigmoid_f(v1[j]); }
;                 u32x2 w; w.x = pk_unorm8(v0); w.y = pk_unorm8(v1);
;                 *(u32x2*)((unsigned char*)P + (size_t)row * ROWB + GATE_B0 + gcol) = w;
	v_pk_mul_f32 v[46:47], v[46:47], v[90:91] op_sel_hi:[1,0]
	v_pk_mul_f32 v[48:49], v[48:49], v[90:91] op_sel_hi:[1,0]
	v_pk_mul_f32 v[42:43], v[42:43], v[90:91] op_sel_hi:[1,0]
	v_pk_mul_f32 v[44:45], v[44:45], v[90:91] op_sel_hi:[1,0]
	v_exp_f32_e32 v46, v46
	v_exp_f32_e32 v47, v47
	v_exp_f32_e32 v48, v48
	v_exp_f32_e32 v49, v49
	v_exp_f32_e32 v42, v42
	v_exp_f32_e32 v43, v43
	v_exp_f32_e32 v44, v44
	v_exp_f32_e32 v45, v45
	v_pk_add_f32 v[46:47], v[46:47], 1.0 op_sel_hi:[1,0]
	v_pk_add_f32 v[48:49], v[48:49], 1.0 op_sel_hi:[1,0]
	v_pk_add_f32 v[42:43], v[42:43], 1.0 op_sel_hi:[1,0]
	v_pk_add_f32 v[44:45], v[44:45], 1.0 op_sel_hi:[1,0]
	v_rcp_f32_e32 v46, v46
	v_rcp_f32_e32 v47, v47
	v_rcp_f32_e32 v48, v48
	v_rcp_f32_e32 v49, v49
	v_rcp_f32_e32 v42, v42
	v_rcp_f32_e32 v43, v43
	v_rcp_f32_e32 v44, v44
	v_rcp_f32_e32 v45, v45
	v_pk_fma_f32 v[46:47], v[46:47], s[98:99], 0.5 op_sel_hi:[1,0,0]
	v_pk_fma_f32 v[48:49], v[48:49], s[98:99], 0.5 op_sel_hi:[1,0,0]
	v_pk_fma_f32 v[42:43], v[42:43], s[98:99], 0.5 op_sel_hi:[1,0,0]
	v_pk_fma_f32 v[44:45], v[44:45], s[98:99], 0.5 op_sel_hi:[1,0,0]
	v_cvt_u32_f32_e32 v170, v46
	v_cvt_u32_f32_e32 v171, v42
	v_cvt_u32_f32_sdwa v170, v47 dst_sel:BYTE_1 dst_unused:UNUSED_PRESERVE src0_sel:DWORD
	v_cvt_u32_f32_sdwa v171, v43 dst_sel:BYTE_1 dst_unused:UNUSED_PRESERVE src0_sel:DWORD
	v_cvt_u32_f32_sdwa v170, v48 dst_sel:BYTE_2 dst_unused:UNUSED_PRESERVE src0_sel:DWORD
	v_cvt_u32_f32_sdwa v171, v44 dst_sel:BYTE_2 dst_unused:UNUSED_PRESERVE src0_sel:DWORD
	v_cvt_u32_f32_sdwa v170, v49 dst_sel:BYTE_3 dst_unused:UNUSED_PRESERVE src0_sel:DWORD
	v_cvt_u32_f32_sdwa v171, v45 dst_sel:BYTE_3 dst_unused:UNUSED_PRESERVE src0_sel:DWORD
	s_nop 1
	global_store_dwordx2 v[174:175], v[170:171], off nt
	v_mad_i64_i32 v[176:177], s[4:5], v93, s33, v[178:179]
	v_pk_mul_f32 v[38:39], v[38:39], v[86:87] op_sel_hi:[1,0]
	v_pk_mul_f32 v[40:41], v[40:41], v[86:87] op_sel_hi:[1,0]
	v_pk_mul_f32 v[34:35], v[34:35], v[86:87] op_sel_hi:[1,0]
	v_pk_mul_f32 v[36:37], v[36:37], v[86:87] op_sel_hi:[1,0]
	v_exp_f32_e32 v38, v38
	v_exp_f32_e32 v39, v39
	v_exp_f32_e32 v40, v40
	v_exp_f32_e32 v41, v41
	v_exp_f32_e32 v34, v34
	v_exp_f32_e32 v35, v35
	v_exp_f32_e32 v36, v36
	v_exp_f32_e32 v37, v37
	v_pk_add_f32 v[38:39], v[38:39], 1.0 op_sel_hi:[1,0]
	v_pk_add_f32 v[40:41], v[40:41], 1.0 op_sel_hi:[1,0]
	v_pk_add_f32 v[34:35], v[34:35], 1.0 op_sel_hi:[1,0]
	v_pk_add_f32 v[36:37], v[36:37], 1.0 op_sel_hi:[1,0]
	v_rcp_f32_e32 v38, v38
	v_rcp_f32_e32 v39, v39
	v_rcp_f32_e32 v40, v40
	v_rcp_f32_e32 v41, v41
	v_rcp_f32_e32 v34, v34
	v_rcp_f32_e32 v35, v35
	v_rcp_f32_e32 v36, v36
	v_rcp_f32_e32 v37, v37
	v_pk_fma_f32 v[38:39], v[38:39], s[98:99], 0.5 op_sel_hi:[1,0,0]
	v_pk_fma_f32 v[40:41], v[40:41], s[98:99], 0.5 op_sel_hi:[1,0,0]
	v_pk_fma_f32 v[34:35], v[34:35], s[98:99], 0.5 op_sel_hi:[1,0,0]
	v_pk_fma_f32 v[36:37], v[36:37], s[98:99], 0.5 op_sel_hi:[1,0,0]
	v_cvt_u32_f32_e32 v172, v38
	v_cvt_u32_f32_e32 v173, v34
	v_cvt_u32_f32_sdwa v172, v39 dst_sel:BYTE_1 dst_unused:UNUSED_PRESERVE src0_sel:DWORD
	v_cvt_u32_f32_sdwa v173, v35 dst_sel:BYTE_1 dst_unused:UNUSED_PRESERVE src0_sel:DWORD
	v_cvt_u32_f32_sdwa v172, v40 dst_sel:BYTE_2 dst_unused:UNUSED_PRESERVE src0_sel:DWORD
	v_cvt_u32_f32_sdwa v173, v36 dst_sel:BYTE_2 dst_unused:UNUSED_PRESERVE src0_sel:DWORD
	v_cvt_u32_f32_sdwa v172, v41 dst_sel:BYTE_3 dst_unused:UNUSED_PRESERVE src0_sel:DWORD
	v_cvt_u32_f32_sdwa v173, v37 dst_sel:BYTE_3 dst_unused:UNUSED_PRESERVE src0_sel:DWORD
	s_nop 1
	global_store_dwordx2 v[176:177], v[172:173], off nt
	v_mad_i64_i32 v[174:175], s[4:5], v91, s33, v[178:179]
	v_pk_mul_f32 v[30:31], v[30:31], v[84:85] op_sel_hi:[1,0]
	v_pk_mul_f32 v[32:33], v[32:33], v[84:85] op_sel_hi:[1,0]
	v_pk_mul_f32 v[26:27], v[26:27], v[84:85] op_sel_hi:[1,0]
	v_pk_mul_f32 v[28:29], v[28:29], v[84:85] op_sel_hi:[1,0]
	v_exp_f32_e32 v30, v30
	v_exp_f32_e32 v31, v31
	v_exp_f32_e32 v32, v32
	v_exp_f32_e32 v33, v33
	v_exp_f32_e32 v26, v26
	v_exp_f32_e32 v27, v27
	v_exp_f32_e32 v28, v28
	v_exp_f32_e32 v29, v29
	v_pk_add_f32 v[30:31], v[30:31], 1.0 op_sel_hi:[1,0]
	v_pk_add_f32 v[32:33], v[32:33], 1.0 op_sel_hi:[1,0]
	v_pk_add_f32 v[26:27], v[26:27], 1.0 op_sel_hi:[1,0]
	v_pk_add_f32 v[28:29], v[28:29], 1.0 op_sel_hi:[1,0]
	v_rcp_f32_e32 v30, v30
	v_rcp_f32_e32 v31, v31
	v_rcp_f32_e32 v32, v32
	v_rcp_f32_e32 v33, v33
	v_rcp_f32_e32 v26, v26
	v_rcp_f32_e32 v27, v27
	v_rcp_f32_e32 v28, v28
	v_rcp_f32_e32 v29, v29
	v_pk_fma_f32 v[30:31], v[30:31], s[98:99], 0.5 op_sel_hi:[1,0,0]
	v_pk_fma_f32 v[32:33], v[32:33], s[98:99], 0.5 op_sel_hi:[1,0,0]
	v_pk_fma_f32 v[26:27], v[26:27], s[98:99], 0.5 op_sel_hi:[1,0,0]
	v_pk_fma_f32 v[28:29], v[28:29], s[98:99], 0.5 op_sel_hi:[1,0,0]
	v_cvt_u32_f32_e32 v170, v30
	v_cvt_u32_f32_e32 v171, v26
	v_cvt_u32_f32_sdwa v170, v31 dst_sel:BYTE_1 dst_unused:UNUSED_PRESERVE src0_sel:DWORD
	v_cvt_u32_f32_sdwa v171, v27 dst_sel:BYTE_1 dst_unused:UNUSED_PRESERVE src0_sel:DWORD
	v_cvt_u32_f32_sdwa v170, v32 dst_sel:BYTE_2 dst_unused:UNUSED_PRESERVE src0_sel:DWORD
	v_cvt_u32_f32_sdwa v171, v28 dst_sel:BYTE_2 dst_unused:UNUSED_PRESERVE src0_sel:DWORD
	v_cvt_u32_f32_sdwa v170, v33 dst_sel:BYTE_3 dst_unused:UNUSED_PRESERVE src0_sel:DWORD
	v_cvt_u32_f32_sdwa v171, v29 dst_sel:BYTE_3 dst_unused:UNUSED_PRESERVE src0_sel:DWORD
	s_nop 1
	global_store_dwordx2 v[174:175], v[170:171], off nt
; __device__ __forceinline__ float sigmoid_f(float x) { return __builtin_amdgcn_rcpf(1.0f + __builtin_amdgcn_exp2f(-1.4426950409f * x)); }
;     __device__ __forceinline__ void body_gate(f32x4 (&acc)[2][2][4][2], const Unit& u, int wr, int wc, int fr, int fq, int gbase, const float (&rsv)[2][4]) const {
;     ...
;             const float rs = rsv[ai][m];
; #pragma unroll
;             for (int bj = 0; bj < 2; ++bj) { if (u.half != 0 && bj == 1) continue;
;                 const int gcol = gbase + (bj + (u.half == 2 ? 1 : 0)) * 128 + wc * 32 + 8 * fq;
;                 f32x4 v0 = acc[ai][bj][m][0] * rs, v1 = acc[ai][bj][m][1] * rs;
; #pragma unroll
;                 for (int j = 0; j < 4; ++j) { v0[j] = sigmoid_f(v0[j]); v1[j] = sigmoid_f(v1[j]); }
;                 u32x2 w; w.x = pk_unorm8(v0); w.y = pk_unorm8(v1);
;                 *(u32x2*)((unsigned char*)P + (size_t)row * ROWB + GATE_B0 + gcol) = w;
	v_mad_i64_i32 v[176:177], s[4:5], v89, s33, v[178:179]
	v_pk_mul_f32 v[22:23], v[22:23], v[82:83] op_sel_hi:[1,0]
	v_pk_mul_f32 v[24:25], v[24:25], v[82:83] op_sel_hi:[1,0]
	v_pk_mul_f32 v[18:19], v[18:19], v[82:83] op_sel_hi:[1,0]
	v_pk_mul_f32 v[20:21], v[20:21], v[82:83] op_sel_hi:[1,0]
	v_exp_f32_e32 v22, v22
	v_exp_f32_e32 v23, v23
	v_exp_f32_e32 v24, v24
	v_exp_f32_e32 v25, v25
	v_exp_f32_e32 v18, v18
	v_exp_f32_e32 v19, v19
	v_exp_f32_e32 v20, v20
	v_exp_f32_e32 v21, v21
	v_pk_add_f32 v[22:23], v[22:23], 1.0 op_sel_hi:[1,0]
	v_pk_add_f32 v[24:25], v[24:25], 1.0 op_sel_hi:[1,0]
	v_pk_add_f32 v[18:19], v[18:19], 1.0 op_sel_hi:[1,0]
	v_pk_add_f32 v[20:21], v[20:21], 1.0 op_sel_hi:[1,0]
	v_rcp_f32_e32 v22, v22
	v_rcp_f32_e32 v23, v23
	v_rcp_f32_e32 v24, v24
	v_rcp_f32_e32 v25, v25
	v_rcp_f32_e32 v18, v18
	v_rcp_f32_e32 v19, v19
	v_rcp_f32_e32 v20, v20
	v_rcp_f32_e32 v21, v21
	v_pk_fma_f32 v[22:23], v[22:23], s[98:99], 0.5 op_sel_hi:[1,0,0]
	v_pk_fma_f32 v[24:25], v[24:25], s[98:99], 0.5 op_sel_hi:[1,0,0]
	v_pk_fma_f32 v[18:19], v[18:19], s[98:99], 0.5 op_sel_hi:[1,0,0]
	v_pk_fma_f32 v[20:21], v[20:21], s[98:99], 0.5 op_sel_hi:[1,0,0]
	v_cvt_u32_f32_e32 v172, v22
	v_cvt_u32_f32_e32 v173, v18
	v_cvt_u32_f32_sdwa v172, v23 dst_sel:BYTE_1 dst_unused:UNUSED_PRESERVE src0_sel:DWORD
	v_cvt_u32_f32_sdwa v173, v19 dst_sel:BYTE_1 dst_unused:UNUSED_PRESERVE src0_sel:DWORD
	v_cvt_u32_f32_sdwa v172, v24 dst_sel:BYTE_2 dst_unused:UNUSED_PRESERVE src0_sel:DWORD
	v_cvt_u32_f32_sdwa v173, v20 dst_sel:BYTE_2 dst_unused:UNUSED_PRESERVE src0_sel:DWORD
	v_cvt_u32_f32_sdwa v172, v25 dst_sel:BYTE_3 dst_unused:UNUSED_PRESERVE src0_sel:DWORD
	v_cvt_u32_f32_sdwa v173, v21 dst_sel:BYTE_3 dst_unused:UNUSED_PRESERVE src0_sel:DWORD
	s_nop 1
	global_store_dwordx2 v[176:177], v[172:173], off nt
	v_mad_i64_i32 v[174:175], s[4:5], v87, s33, v[178:179]
	v_pk_mul_f32 v[14:15], v[14:15], v[80:81] op_sel_hi:[1,0]
	v_pk_mul_f32 v[16:17], v[16:17], v[80:81] op_sel_hi:[1,0]
	v_pk_mul_f32 v[10:11], v[10:11], v[80:81] op_sel_hi:[1,0]
	v_pk_mul_f32 v[12:13], v[12:13], v[80:81] op_sel_hi:[1,0]
	v_exp_f32_e32 v14, v14
	v_exp_f32_e32 v15, v15
	v_exp_f32_e32 v16, v16
	v_exp_f32_e32 v17, v17
	v_exp_f32_e32 v10, v10
	v_exp_f32_e32 v11, v11
	v_exp_f32_e32 v12, v12
	v_exp_f32_e32 v13, v13
	v_pk_add_f32 v[14:15], v[14:15], 1.0 op_sel_hi:[1,0]
	v_pk_add_f32 v[16:17], v[16:17], 1.0 op_sel_hi:[1,0]
	v_pk_add_f32 v[10:11], v[10:11], 1.0 op_sel_hi:[1,0]
	v_pk_add_f32 v[12:13], v[12:13], 1.0 op_sel_hi:[1,0]
	v_rcp_f32_e32 v14, v14
	v_rcp_f32_e32 v15, v15
	v_rcp_f32_e32 v16, v16
	v_rcp_f32_e32 v17, v17
	v_rcp_f32_e32 v10, v10
	v_rcp_f32_e32 v11, v11
	v_rcp_f32_e32 v12, v12
	v_rcp_f32_e32 v13, v13
	v_pk_fma_f32 v[14:15], v[14:15], s[98:99], 0.5 op_sel_hi:[1,0,0]
	v_pk_fma_f32 v[16:17], v[16:17], s[98:99], 0.5 op_sel_hi:[1,0,0]
	v_pk_fma_f32 v[10:11], v[10:11], s[98:99], 0.5 op_sel_hi:[1,0,0]
	v_pk_fma_f32 v[12:13], v[12:13], s[98:99], 0.5 op_sel_hi:[1,0,0]
	v_cvt_u32_f32_e32 v170, v14
	v_cvt_u32_f32_e32 v171, v10
	v_cvt_u32_f32_sdwa v170, v15 dst_sel:BYTE_1 dst_unused:UNUSED_PRESERVE src0_sel:DWORD
	v_cvt_u32_f32_sdwa v171, v11 dst_sel:BYTE_1 dst_unused:UNUSED_PRESERVE src0_sel:DWORD
	v_cvt_u32_f32_sdwa v170, v16 dst_sel:BYTE_2 dst_unused:UNUSED_PRESERVE src0_sel:DWORD
	v_cvt_u32_f32_sdwa v171, v12 dst_sel:BYTE_2 dst_unused:UNUSED_PRESERVE src0_sel:DWORD
	v_cvt_u32_f32_sdwa v170, v17 dst_sel:BYTE_3 dst_unused:UNUSED_PRESERVE src0_sel:DWORD
	v_cvt_u32_f32_sdwa v171, v13 dst_sel:BYTE_3 dst_unused:UNUSED_PRESERVE src0_sel:DWORD
	s_nop 1
	global_store_dwordx2 v[174:175], v[170:171], off nt
	v_mad_i64_i32 v[176:177], s[4:5], v85, s33, v[178:179]
	v_pk_mul_f32 v[6:7], v[6:7], v[78:79] op_sel_hi:[1,0]
	v_pk_mul_f32 v[8:9], v[8:9], v[78:79] op_sel_hi:[1,0]
	v_pk_mul_f32 v[2:3], v[2:3], v[78:79] op_sel_hi:[1,0]
	v_pk_mul_f32 v[4:5], v[4:5], v[78:79] op_sel_hi:[1,0]
	v_exp_f32_e32 v6, v6
	v_exp_f32_e32 v7, v7
	v_exp_f32_e32 v8, v8
	v_exp_f32_e32 v9, v9
	v_exp_f32_e32 v2, v2
	v_exp_f32_e32 v3, v3
	v_exp_f32_e32 v4, v4
	v_exp_f32_e32 v5, v5
	v_pk_add_f32 v[6:7], v[6:7], 1.0 op_sel_hi:[1,0]
	v_pk_add_f32 v[8:9], v[8:9], 1.0 op_sel_hi:[1,0]
	v_pk_add_f32 v[2:3], v[2:3], 1.0 op_sel_hi:[1,0]
	v_pk_add_f32 v[4:5], v[4:5], 1.0 op_sel_hi:[1,0]
	v_rcp_f32_e32 v6, v6
	v_rcp_f32_e32 v7, v7
	v_rcp_f32_e32 v8, v8
	v_rcp_f32_e32 v9, v9
	v_rcp_f32_e32 v2, v2
	v_rcp_f32_e32 v3, v3
	v_rcp_f32_e32 v4, v4
	v_rcp_f32_e32 v5, v5
	v_pk_fma_f32 v[6:7], v[6:7], s[98:99], 0.5 op_sel_hi:[1,0,0]
	v_pk_fma_f32 v[8:9], v[8:9], s[98:99], 0.5 op_sel_hi:[1,0,0]
	v_pk_fma_f32 v[2:3], v[2:3], s[98:99], 0.5 op_sel_hi:[1,0,0]
	v_pk_fma_f32 v[4:5], v[4:5], s[98:99], 0.5 op_sel_hi:[1,0,0]
	v_cvt_u32_f32_e32 v172, v6
	v_cvt_u32_f32_e32 v173, v2
	v_cvt_u32_f32_sdwa v172, v7 dst_sel:BYTE_1 dst_unused:UNUSED_PRESERVE src0_sel:DWORD
	v_cvt_u32_f32_sdwa v173, v3 dst_sel:BYTE_1 dst_unused:UNUSED_PRESERVE src0_sel:DWORD
	v_cvt_u32_f32_sdwa v172, v8 dst_sel:BYTE_2 dst_unused:UNUSED_PRESERVE src0_sel:DWORD
	v_cvt_u32_f32_sdwa v173, v4 dst_sel:BYTE_2 dst_unused:UNUSED_PRESERVE src0_sel:DWORD
	v_cvt_u32_f32_sdwa v172, v9 dst_sel:BYTE_3 dst_unused:UNUSED_PRESERVE src0_sel:DWORD
	v_cvt_u32_f32_sdwa v173, v5 dst_sel:BYTE_3 dst_unused:UNUSED_PRESERVE src0_sel:DWORD
	s_nop 1
	global_store_dwordx2 v[176:177], v[172:173], off nt
	s_mov_b64 s[4:5], 0
